# tail16 restructured: both 16x16 tail tiles of a block processed at once (waves 0-3 / 4-7), all operand loads in flight, one reduce pass
# baseline (speedup 1.0000x reference)
; DI void gemm_run(const GemmCfg c, char* smem, float* const g_h, u16* const g_hb, float* const g_out, const int final_out) {
;     ...
;   if (tail16) {
;     float* sP = (float*)smem;
;     const int l15 = lane & 15, kq = lane >> 4;
;     const int Kw = K >> 3;
;     for (int t = (int)blockIdx.x; t < 512; t += G) {
;       const int rg = t & 7, cg = t >> 3;
;       const u16* Ap = c.A + (size_t)(16384 + rg * 16 + l15) * c.lda + (cg >> 4) * c.a_koff_tn + w * Kw + kq * 8;
;       const u16* Bp = c.Bt + (size_t)(cg * 16 + l15) * K + w * Kw + kq * 8;
;       const size_t erow = 16384 + rg * 16 + ((tid & 255) >> 4);
;       const int ecol = cg * 16 + (tid & 15);
;       float hpre = 0.f;
;       if (c.epi == EPI_RESID) hpre = g_h[erow * D + ecol];
;       f32x4 a4 = {0.f, 0.f, 0.f, 0.f};
.LBB0_433:
	v_readlane_b32 s0, v255, 20
	v_readlane_b32 s1, v255, 21
	v_readlane_b32 s72, v255, 9
	s_and_b64 vcc, exec, s[0:1]
	v_readlane_b32 s73, v255, 10
	s_waitcnt lgkmcnt(0)
	s_barrier
	s_cbranch_vccz .LBB0_454
	v_readlane_b32 s0, v252, 25
	v_readlane_b32 s1, v252, 26
	s_andn2_b64 vcc, exec, s[0:1]
	s_cbranch_vccnz .LBB0_454
	s_ashr_i32 s0, s60, 2
	v_readlane_b32 s1, v255, 15
	s_and_b32 s6, s1, 3
	s_mul_i32 s6, s6, s0
	s_ashr_i32 s7, s6, 31
	s_ashr_i32 s63, s62, 31
	s_ashr_i32 s61, s60, 31
	s_lshl_b64 s[18:19], s[6:7], 1
	v_readlane_b32 s16, v255, 5
	v_readlane_b32 s17, v255, 6
	s_add_u32 s4, s16, s18
	s_addc_u32 s5, s17, s19
	s_cmpk_lg_i32 s0, 0x2c0
	s_cselect_b64 s[8:9], -1, 0
	s_cmp_gt_i32 s0, 0
	s_waitcnt vmcnt(17)
	v_and_b32_e32 v18, 15, v184
	v_lshrrev_b32_e32 v1, 4, v185
	v_and_b32_e32 v164, 48, v185
	s_cselect_b64 s[14:15], -1, 0
	s_lshl_b32 s1, s1, 10
	v_lshlrev_b32_e32 v0, 3, v1
	v_lshl_add_u64 v[4:5], s[4:5], 0, v[164:165]
	v_lshlrev_b32_e32 v1, 8, v1
	v_lshlrev_b32_e32 v2, 2, v18
	s_cmpk_eq_i32 s60, 0xb00
	v_and_b32_e32 v164, 48, v184
	s_waitcnt vmcnt(16)
	v_or3_b32 v20, s1, v1, v2
	s_movk_i32 s1, 0x200
	s_cselect_b64 s[20:21], -1, 0
	v_lshl_add_u64 v[2:3], v[164:165], 0, s[18:19]
	v_readlane_b32 s22, v252, 0
	v_readlane_b32 s46, v255, 18
	v_readlane_b32 s48, v255, 16
	v_bfe_u32 v19, v184, 4, 4
	v_cmp_gt_i32_e64 s[4:5], s1, v184
	v_lshlrev_b32_e32 v21, 2, v184
	v_and_b32_e32 v26, 0x100, v184
	v_mul_u32_u24_e32 v26, 12, v26
	v_add_u32_e32 v21, v21, v26
	v_cndmask_b32_e64 v22, 1.0, 0.5, s[20:21]
	v_lshl_add_u64 v[6:7], s[54:55], 0, v[2:3]
	s_lshl_b64 s[18:19], s[62:63], 1
	v_or_b32_e32 v23, 0x4000, v18
	v_lshl_add_u64 v[8:9], s[16:17], 0, v[2:3]
	s_lshl_b64 s[20:21], s[60:61], 1
	v_lshlrev_b32_e32 v10, 1, v0
	v_readlane_b32 s1, v254, 22
	v_readlane_b32 s30, v254, 21
	s_mov_b32 s40, s22
	v_readlane_b32 s44, v255, 11
	v_readlane_b32 s47, v255, 19
	v_readlane_b32 s49, v255, 17
	v_readlane_b32 s23, v252, 1
	v_readlane_b32 s45, v255, 12
	v_readlane_b32 s26, v255, 15
	s_nop 1
	s_lshr_b32 s26, s26, 2
	s_lshl_b32 s27, s26, 8
	s_add_i32 s40, s40, s27
	s_lshl_b32 s27, s26, 12
	s_add_i32 s30, s30, s27
	s_lshl_b32 s27, s26, 9
	s_add_i32 s1, s1, s27
	s_branch .LBB0_437
.LBB0_436:
	s_or_b64 exec, exec, s[22:23]
	s_add_i32 s22, s40, 0x100
	s_addk_i32 s30, 0x1000
	s_addk_i32 s1, 0x200
	s_cmpk_lt_i32 s40, 0x100
	s_mov_b32 s40, s22
	s_barrier
	s_branch .LBB0_454

; DI f32x4 mfma16(bf16x8 a, bf16x8 b, f32x4 c) { return __builtin_amdgcn_mfma_f32_16x16x32_bf16(a, b, c, 0, 0, 0); }
; DI void gemm_run(const GemmCfg c, char* smem, float* const g_h, u16* const g_hb, float* const g_out, const int final_out) {
;     ...
;       } else {
; #pragma unroll 4
;         for (int k = 0; k < Kw; k += 32) {
;           bf16x8 av = *(const bf16x8*)(Ap + k);
;           bf16x8 bv = *(const bf16x8*)(Bp + k);
;           a4 = mfma16(av, bv, a4);
;         }
;       }
.LBB0_439:
	s_ashr_i32 s22, s40, 7
	s_mul_i32 s22, s22, s2
	s_ashr_i32 s23, s22, 31
	s_mov_b64 s[26:27], -1
	s_and_b64 vcc, exec, s[8:9]
	s_cbranch_vccz .LBB0_445
	s_andn2_b64 vcc, exec, s[14:15]
	s_cbranch_vccnz .LBB0_443
	s_and_b32 s26, s30, 0x70
	v_and_or_b32 v0, s1, -16, v18
	v_add_u32_e32 v2, s26, v23
	s_ashr_i32 s42, s1, 31
	v_mad_u64_u32 v[14:15], s[26:27], s20, v0, v[8:9]
	v_mul_lo_u32 v1, s21, v0
	s_mul_i32 s26, s20, s42
	v_add3_u32 v15, v1, v15, s26
	s_lshl_b64 s[26:27], s[22:23], 1
	v_mov_b64_e32 v[0:1], s[26:27]
	v_mad_u64_u32 v[0:1], s[26:27], s18, v2, v[0:1]
	v_mad_i32_i24 v1, s19, v2, v1
	v_lshl_add_u64 v[16:17], v[6:7], 0, v[0:1]
	v_mov_b32_e32 v0, 0
	s_mov_b32 s26, 0
	v_mov_b32_e32 v1, v0
	v_mov_b32_e32 v2, v0
	v_mov_b32_e32 v3, v0
	s_cmpk_lg_i32 s0, 0x100
	s_cbranch_scc1 .LBB0_442
	global_load_dwordx4 v[36:39], v[16:17], off
	global_load_dwordx4 v[40:43], v[14:15], off
	global_load_dwordx4 v[44:47], v[16:17], off offset:64
	global_load_dwordx4 v[48:51], v[14:15], off offset:64
	global_load_dwordx4 v[52:55], v[16:17], off offset:128
	global_load_dwordx4 v[56:59], v[14:15], off offset:128
	global_load_dwordx4 v[60:63], v[16:17], off offset:192
	global_load_dwordx4 v[64:67], v[14:15], off offset:192
	global_load_dwordx4 v[68:71], v[16:17], off offset:256
	global_load_dwordx4 v[72:75], v[14:15], off offset:256
	global_load_dwordx4 v[76:79], v[16:17], off offset:320
	global_load_dwordx4 v[80:83], v[14:15], off offset:320
	global_load_dwordx4 v[84:87], v[16:17], off offset:384
	global_load_dwordx4 v[88:91], v[14:15], off offset:384
	global_load_dwordx4 v[92:95], v[16:17], off offset:448
	global_load_dwordx4 v[96:99], v[14:15], off offset:448
	s_waitcnt vmcnt(14)
	v_mfma_f32_16x16x32_bf16 v[0:3], v[36:39], v[40:43], v[0:3]
	s_waitcnt vmcnt(12)
	v_mfma_f32_16x16x32_bf16 v[0:3], v[44:47], v[48:51], v[0:3]
	s_waitcnt vmcnt(10)
	v_mfma_f32_16x16x32_bf16 v[0:3], v[52:55], v[56:59], v[0:3]
	s_waitcnt vmcnt(8)
	v_mfma_f32_16x16x32_bf16 v[0:3], v[60:63], v[64:67], v[0:3]
	s_waitcnt vmcnt(6)
	v_mfma_f32_16x16x32_bf16 v[0:3], v[68:71], v[72:75], v[0:3]
	s_waitcnt vmcnt(4)
	v_mfma_f32_16x16x32_bf16 v[0:3], v[76:79], v[80:83], v[0:3]
	s_waitcnt vmcnt(2)
	v_mfma_f32_16x16x32_bf16 v[0:3], v[84:87], v[88:91], v[0:3]
	s_waitcnt vmcnt(0)
	v_mfma_f32_16x16x32_bf16 v[0:3], v[92:95], v[96:99], v[0:3]
	s_branch .LBB0_444

; DI f32x4 mfma16(bf16x8 a, bf16x8 b, f32x4 c) { return __builtin_amdgcn_mfma_f32_16x16x32_bf16(a, b, c, 0, 0, 0); }
; DI void gemm_run(const GemmCfg c, char* smem, float* const g_h, u16* const g_hb, float* const g_out, const int final_out) {
;     ...
;       if (Kw == 352) {
; #pragma unroll
;         for (int k = 0; k < 352; k += 32) {
;           bf16x8 av = *(const bf16x8*)(Ap + k);
;           bf16x8 bv = *(const bf16x8*)(Bp + k);
;           a4 = mfma16(av, bv, a4);
;         }
;     ...
; #pragma unroll
;       for (int i = 0; i < 4; ++i) sP[w * 256 + (kq * 4 + i) * 16 + l15] = a4[i];
;       __syncthreads();
;       if (tid < 256) {
;         const float v = ((sP[tid] + sP[256 + tid]) + (sP[512 + tid] + sP[768 + tid])) + ((sP[1024 + tid] + sP[1280 + tid]) + (sP[1536 + tid] + sP[1792 + tid]));
;         const size_t row = erow;
;         const int col = ecol;
;         if (c.epi == EPI_RESID) {
;           const float o = hpre + v * (K == DFF ? 0.5f : 1.f);
;           g_h[row * D + col] = o;
;           g_hb[row * D + col] = (u16)(pack2(o, o) & 0xffffu);
;           if (final_out) {
;             const int b = (int)(row / T), t2 = (int)(row % T);
;             if (t2 >= 16) g_out[((size_t)b * 2048 + (t2 - 16)) * D + col] = o;
;           }
;         } else {
;           c.o16[row * c.ldo + col] = (u16)(pack2(v, v) & 0xffffu);
;         }
.LBB0_445:
	s_andn2_b64 vcc, exec, s[26:27]
	s_cbranch_vccnz .LBB0_447
	s_nop 2
	v_or_b32_e32 v0, s41, v18
	v_mad_i64_i32 v[0:1], s[26:27], v0, s62, 0
	v_lshl_add_u64 v[0:1], v[0:1], 1, s[54:55]
	v_lshl_add_u64 v[0:1], s[22:23], 1, v[0:1]
	v_lshl_add_u64 v[0:1], s[6:7], 1, v[0:1]
	v_mov_b32_e32 v11, v165
	v_lshl_add_u64 v[30:31], v[0:1], 0, v[10:11]
	v_mad_i64_i32 v[0:1], s[22:23], v12, s60, 0
	v_lshl_add_u64 v[32:33], v[0:1], 1, v[4:5]
	global_load_dwordx4 v[36:39], v[30:31], off
	global_load_dwordx4 v[40:43], v[32:33], off
	global_load_dwordx4 v[44:47], v[30:31], off offset:64
	global_load_dwordx4 v[48:51], v[32:33], off offset:64
	global_load_dwordx4 v[52:55], v[30:31], off offset:128
	global_load_dwordx4 v[56:59], v[32:33], off offset:128
	global_load_dwordx4 v[60:63], v[30:31], off offset:192
	global_load_dwordx4 v[64:67], v[32:33], off offset:192
	global_load_dwordx4 v[68:71], v[30:31], off offset:256
	global_load_dwordx4 v[72:75], v[32:33], off offset:256
	global_load_dwordx4 v[76:79], v[30:31], off offset:320
	global_load_dwordx4 v[80:83], v[32:33], off offset:320
	global_load_dwordx4 v[84:87], v[30:31], off offset:384
	global_load_dwordx4 v[88:91], v[32:33], off offset:384
	global_load_dwordx4 v[92:95], v[30:31], off offset:448
	global_load_dwordx4 v[96:99], v[32:33], off offset:448
	global_load_dwordx4 v[100:103], v[30:31], off offset:512
	global_load_dwordx4 v[104:107], v[32:33], off offset:512
	global_load_dwordx4 v[108:111], v[30:31], off offset:576
	global_load_dwordx4 v[112:115], v[32:33], off offset:576
	global_load_dwordx4 v[116:119], v[30:31], off offset:640
	global_load_dwordx4 v[120:123], v[32:33], off offset:640
	global_load_dwordx4 v[124:127], v[30:31], off offset:704
	global_load_dwordx4 v[128:131], v[32:33], off offset:704
	global_load_dwordx4 v[132:135], v[30:31], off offset:768
	global_load_dwordx4 v[136:139], v[32:33], off offset:768
	global_load_dwordx4 v[140:143], v[30:31], off offset:832
	global_load_dwordx4 v[144:147], v[32:33], off offset:832
	global_load_dwordx4 v[148:151], v[30:31], off offset:896
	global_load_dwordx4 v[152:155], v[32:33], off offset:896
	global_load_dwordx4 v[156:159], v[30:31], off offset:960
	global_load_dwordx4 v[160:163], v[32:33], off offset:960
	global_load_dwordx4 v[176:179], v[30:31], off offset:1024
	global_load_dwordx4 v[180:183], v[32:33], off offset:1024
	global_load_dwordx4 v[192:195], v[30:31], off offset:1088
	global_load_dwordx4 v[200:203], v[32:33], off offset:1088
	global_load_dwordx4 v[204:207], v[30:31], off offset:1152
	global_load_dwordx4 v[222:225], v[32:33], off offset:1152
	global_load_dwordx4 v[226:229], v[30:31], off offset:1216
	global_load_dwordx4 v[230:233], v[32:33], off offset:1216
	global_load_dwordx4 v[234:237], v[30:31], off offset:1280
	global_load_dwordx4 v[238:241], v[32:33], off offset:1280
	global_load_dwordx4 v[242:245], v[30:31], off offset:1344
	global_load_dwordx4 v[246:249], v[32:33], off offset:1344
	s_waitcnt vmcnt(42)
	v_mfma_f32_16x16x32_bf16 v[0:3], v[36:39], v[40:43], 0
	s_waitcnt vmcnt(40)
	v_mfma_f32_16x16x32_bf16 v[0:3], v[44:47], v[48:51], v[0:3]
	s_waitcnt vmcnt(38)
	v_mfma_f32_16x16x32_bf16 v[0:3], v[52:55], v[56:59], v[0:3]
	s_waitcnt vmcnt(36)
	v_mfma_f32_16x16x32_bf16 v[0:3], v[60:63], v[64:67], v[0:3]
	s_waitcnt vmcnt(34)
	v_mfma_f32_16x16x32_bf16 v[0:3], v[68:71], v[72:75], v[0:3]
	s_waitcnt vmcnt(32)
	v_mfma_f32_16x16x32_bf16 v[0:3], v[76:79], v[80:83], v[0:3]
	s_waitcnt vmcnt(30)
	v_mfma_f32_16x16x32_bf16 v[0:3], v[84:87], v[88:91], v[0:3]
	s_waitcnt vmcnt(28)
	v_mfma_f32_16x16x32_bf16 v[0:3], v[92:95], v[96:99], v[0:3]
	s_waitcnt vmcnt(26)
	v_mfma_f32_16x16x32_bf16 v[0:3], v[100:103], v[104:107], v[0:3]
	s_waitcnt vmcnt(24)
	v_mfma_f32_16x16x32_bf16 v[0:3], v[108:111], v[112:115], v[0:3]
	s_waitcnt vmcnt(22)
	v_mfma_f32_16x16x32_bf16 v[0:3], v[116:119], v[120:123], v[0:3]
	s_waitcnt vmcnt(20)
	v_mfma_f32_16x16x32_bf16 v[0:3], v[124:127], v[128:131], v[0:3]
	s_waitcnt vmcnt(18)
	v_mfma_f32_16x16x32_bf16 v[0:3], v[132:135], v[136:139], v[0:3]
	s_waitcnt vmcnt(16)
	v_mfma_f32_16x16x32_bf16 v[0:3], v[140:143], v[144:147], v[0:3]
	s_waitcnt vmcnt(14)
	v_mfma_f32_16x16x32_bf16 v[0:3], v[148:151], v[152:155], v[0:3]
	s_waitcnt vmcnt(12)
	v_mfma_f32_16x16x32_bf16 v[0:3], v[156:159], v[160:163], v[0:3]
	s_waitcnt vmcnt(10)
	v_mfma_f32_16x16x32_bf16 v[0:3], v[176:179], v[180:183], v[0:3]
	s_waitcnt vmcnt(8)
	v_mfma_f32_16x16x32_bf16 v[0:3], v[192:195], v[200:203], v[0:3]
	s_waitcnt vmcnt(6)
	v_mfma_f32_16x16x32_bf16 v[0:3], v[204:207], v[222:225], v[0:3]
	s_waitcnt vmcnt(4)
	v_mfma_f32_16x16x32_bf16 v[0:3], v[226:229], v[230:233], v[0:3]
	s_waitcnt vmcnt(2)
	v_mfma_f32_16x16x32_bf16 v[0:3], v[234:237], v[238:241], v[0:3]
	s_waitcnt vmcnt(0)
	v_mfma_f32_16x16x32_bf16 v[0:3], v[242:245], v[246:249], v[0:3]
.LBB0_447:
	s_nop 7
	ds_write2_b32 v20, v0, v1 offset1:16
	ds_write2_b32 v20, v2, v3 offset0:32 offset1:48
	s_waitcnt lgkmcnt(0)
	s_barrier
	s_and_saveexec_b64 s[22:23], s[4:5]
	s_cbranch_execz .LBB0_436
	ds_read2st64_b32 v[0:1], v21 offset1:4
	s_mov_b64 s[26:27], -1
	s_and_b64 vcc, exec, s[48:49]
	s_waitcnt lgkmcnt(0)
	v_add_f32_e32 v2, v0, v1
	ds_read2st64_b32 v[0:1], v21 offset0:8 offset1:12
	s_waitcnt lgkmcnt(0)
	v_add_f32_e32 v0, v0, v1
	v_add_f32_e32 v2, v2, v0
	v_mov_b32_e32 v0, v2
	s_cbranch_vccz .LBB0_450
	v_mad_i64_i32 v[2:3], s[26:27], v25, s44, 0
	v_lshl_add_u64 v[2:3], v[2:3], 1, s[56:57]
	v_cvt_pk_bf16_f32 v1, v0, s0
	v_lshl_add_u64 v[2:3], v[12:13], 1, v[2:3]
	global_store_short v[2:3], v1, off
	s_mov_b64 s[26:27], 0
